# speedup vs baseline: 1.0050x; 1.0050x over previous
; __device__ __forceinline__ unsigned cvtpk(float lo, float hi) { f32x2 v = {lo, hi}; bf16x2_t b = __builtin_convertvector(v, bf16x2_t); return __builtin_bit_cast(unsigned, b); }
; template <int MODE>
; __device__ __forceinline__ void attn_unit(const UnitP& P, ALAS char* lds, const float* __restrict__ sub_gain, const int wv0, unsigned& hgen, unsigned* qctr, const int xcd) {
;     ...
;         const int th = wl * 64 + lane;
; #pragma unroll 1
;         for (int mtx = 0; mtx < 2; ++mtx) {
;             const float* src = mtx == 0 ? P.cvK : P.cvV; bf16_t* dst = const_cast<bf16_t*>(mtx == 0 ? P.K : P.V);
; #pragma unroll 1
;             for (int p0 = th; p0 < 16384; p0 += 1024) {
;                 f32x4 a[4], b[4];
; #pragma unroll
;                 for (int u = 0; u < 4; ++u) { const int p = p0 + 256 * u; const float* sp = src + (size_t)(p >> 4) * 1024 + (p & 15) * 8; a[u] = __builtin_nontemporal_load((const f32x4*)sp); b[u] = __builtin_nontemporal_load((const f32x4*)(sp + 4)); }
; #pragma unroll
;                 for (int u = 0; u < 4; ++u) { const int p = p0 + 256 * u;
;                     u32x4 w; w.x = cvtpk(a[u][0], a[u][1]); w.y = cvtpk(a[u][2], a[u][3]); w.z = cvtpk(b[u][0], b[u][1]); w.w = cvtpk(b[u][2], b[u][3]);
;                     *(u32x4*)(dst + (size_t)(p >> 4) * 1024 + (p & 15) * 8) = w; }
;             }
.LBB0_253:
	s_xor_b64 s[4:5], s[6:7], -1
	s_and_b64 s[6:7], s[6:7], exec
	s_cselect_b32 s6, s92, s84
	s_cselect_b32 s7, s93, s85
	s_cselect_b32 s9, s1, s87
	s_cselect_b32 s8, s0, s86
	s_add_u32 s10, s6, 16
	s_addc_u32 s11, s7, 0
	v_lshl_add_u64 v[16:17], s[8:9], 0, v[176:177]
	v_lshl_add_u64 v[18:19], s[10:11], 0, v[2:3]
	v_lshl_add_u64 v[20:21], s[8:9], 0, v[4:5]
	v_lshl_add_u64 v[22:23], s[6:7], 0, v[6:7]
	v_lshl_add_u64 v[24:25], s[10:11], 0, v[8:9]
	v_lshl_add_u64 v[26:27], s[8:9], 0, v[10:11]
	v_lshl_add_u64 v[28:29], s[8:9], 0, v[12:13]
	v_lshl_add_u64 v[30:31], s[10:11], 0, v[14:15]
	s_mov_b64 s[6:7], 0
	v_mov_b32_e32 v34, v33
	v_lshl_add_u64 v[40:41], v[22:23], 0, v[0:1]
	v_lshl_add_u64 v[48:49], v[30:31], 0, v[0:1]
	v_lshl_add_u64 v[56:57], v[24:25], 0, v[0:1]
	v_lshl_add_u64 v[64:65], v[18:19], 0, v[0:1]
	global_load_dwordx4 v[36:39], v[40:41], off nt
	s_nop 0
	global_load_dwordx4 v[40:43], v[40:41], off offset:16 nt
	s_nop 0
	global_load_dwordx4 v[44:47], v[48:49], off offset:-16 nt
	s_nop 0
	global_load_dwordx4 v[48:51], v[48:49], off nt
	s_nop 0
	global_load_dwordx4 v[52:55], v[56:57], off offset:-16 nt
	s_nop 0
	global_load_dwordx4 v[56:59], v[56:57], off nt
	s_nop 0
	global_load_dwordx4 v[60:63], v[64:65], off offset:-16 nt
	s_nop 0
	global_load_dwordx4 v[64:67], v[64:65], off nt
	v_lshl_add_u64 v[22:23], v[22:23], 0, s[78:79]
	v_lshl_add_u64 v[30:31], v[30:31], 0, s[78:79]
	v_lshl_add_u64 v[24:25], v[24:25], 0, s[78:79]
	v_lshl_add_u64 v[18:19], v[18:19], 0, s[78:79]
	v_lshl_add_u64 v[72:73], v[22:23], 0, v[0:1]
	v_lshl_add_u64 v[80:81], v[30:31], 0, v[0:1]
	v_lshl_add_u64 v[88:89], v[24:25], 0, v[0:1]
	v_lshl_add_u64 v[96:97], v[18:19], 0, v[0:1]
	global_load_dwordx4 v[68:71], v[72:73], off nt
	s_nop 0
	global_load_dwordx4 v[72:75], v[72:73], off offset:16 nt
	s_nop 0
	global_load_dwordx4 v[76:79], v[80:81], off offset:-16 nt
	s_nop 0
	global_load_dwordx4 v[80:83], v[80:81], off nt
	s_nop 0
	global_load_dwordx4 v[84:87], v[88:89], off offset:-16 nt
	s_nop 0
	global_load_dwordx4 v[88:91], v[88:89], off nt
	s_nop 0
	global_load_dwordx4 v[92:95], v[96:97], off offset:-16 nt
	s_nop 0
	global_load_dwordx4 v[96:99], v[96:97], off nt
	v_lshl_add_u64 v[22:23], v[22:23], 0, s[78:79]
	v_lshl_add_u64 v[30:31], v[30:31], 0, s[78:79]
	v_lshl_add_u64 v[24:25], v[24:25], 0, s[78:79]
	v_lshl_add_u64 v[18:19], v[18:19], 0, s[78:79]
	s_waitcnt vmcnt(8)
	v_cvt_pk_bf16_f32 v36, v36, v37
	v_cvt_pk_bf16_f32 v37, v38, v39
	v_cvt_pk_bf16_f32 v38, v40, v41
	v_cvt_pk_bf16_f32 v39, v42, v43
	v_cvt_pk_bf16_f32 v40, v44, v45
	v_cvt_pk_bf16_f32 v41, v46, v47
	v_cvt_pk_bf16_f32 v42, v48, v49
	v_cvt_pk_bf16_f32 v43, v50, v51
	v_cvt_pk_bf16_f32 v44, v52, v53
	v_cvt_pk_bf16_f32 v45, v54, v55
	v_cvt_pk_bf16_f32 v46, v56, v57
	v_cvt_pk_bf16_f32 v47, v58, v59
	v_cvt_pk_bf16_f32 v48, v60, v61
	v_cvt_pk_bf16_f32 v49, v62, v63
	v_cvt_pk_bf16_f32 v50, v64, v65
	v_cvt_pk_bf16_f32 v51, v66, v67
	global_store_dwordx4 v[16:17], v[36:39], off
	global_store_dwordx4 v[28:29], v[40:43], off
	global_store_dwordx4 v[26:27], v[44:47], off
	global_store_dwordx4 v[20:21], v[48:51], off
	v_lshl_add_u64 v[16:17], v[16:17], 0, s[98:99]
	v_lshl_add_u64 v[28:29], v[28:29], 0, s[98:99]
	v_lshl_add_u64 v[26:27], v[26:27], 0, s[98:99]
	v_lshl_add_u64 v[20:21], v[20:21], 0, s[98:99]
	s_mov_b32 s6, 7
; __device__ __forceinline__ unsigned cvtpk(float lo, float hi) { f32x2 v = {lo, hi}; bf16x2_t b = __builtin_convertvector(v, bf16x2_t); return __builtin_bit_cast(unsigned, b); }
; template <int MODE>
; __device__ __forceinline__ void attn_unit(const UnitP& P, ALAS char* lds, const float* __restrict__ sub_gain, const int wv0, unsigned& hgen, unsigned* qctr, const int xcd) {
;     ...
;             for (int p0 = th; p0 < 16384; p0 += 1024) {
;                 f32x4 a[4], b[4];
; #pragma unroll
;                 for (int u = 0; u < 4; ++u) { const int p = p0 + 256 * u; const float* sp = src + (size_t)(p >> 4) * 1024 + (p & 15) * 8; a[u] = __builtin_nontemporal_load((const f32x4*)sp); b[u] = __builtin_nontemporal_load((const f32x4*)(sp + 4)); }
; #pragma unroll
;                 for (int u = 0; u < 4; ++u) { const int p = p0 + 256 * u;
;                     u32x4 w; w.x = cvtpk(a[u][0], a[u][1]); w.y = cvtpk(a[u][2], a[u][3]); w.z = cvtpk(b[u][0], b[u][1]); w.w = cvtpk(b[u][2], b[u][3]);
;                     *(u32x4*)(dst + (size_t)(p >> 4) * 1024 + (p & 15) * 8) = w; }
.Lcv0_loop:
	v_lshl_add_u64 v[40:41], v[22:23], 0, v[0:1]
	v_lshl_add_u64 v[48:49], v[30:31], 0, v[0:1]
	v_lshl_add_u64 v[56:57], v[24:25], 0, v[0:1]
	v_lshl_add_u64 v[64:65], v[18:19], 0, v[0:1]
	global_load_dwordx4 v[36:39], v[40:41], off nt
	s_nop 0
	global_load_dwordx4 v[40:43], v[40:41], off offset:16 nt
	s_nop 0
	global_load_dwordx4 v[44:47], v[48:49], off offset:-16 nt
	s_nop 0
	global_load_dwordx4 v[48:51], v[48:49], off nt
	s_nop 0
	global_load_dwordx4 v[52:55], v[56:57], off offset:-16 nt
	s_nop 0
	global_load_dwordx4 v[56:59], v[56:57], off nt
	s_nop 0
	global_load_dwordx4 v[60:63], v[64:65], off offset:-16 nt
	s_nop 0
	global_load_dwordx4 v[64:67], v[64:65], off nt
	v_lshl_add_u64 v[22:23], v[22:23], 0, s[78:79]
	v_lshl_add_u64 v[30:31], v[30:31], 0, s[78:79]
	v_lshl_add_u64 v[24:25], v[24:25], 0, s[78:79]
	v_lshl_add_u64 v[18:19], v[18:19], 0, s[78:79]
	s_waitcnt vmcnt(8)
	v_cvt_pk_bf16_f32 v68, v68, v69
	v_cvt_pk_bf16_f32 v69, v70, v71
	v_cvt_pk_bf16_f32 v70, v72, v73
	v_cvt_pk_bf16_f32 v71, v74, v75
	v_cvt_pk_bf16_f32 v72, v76, v77
	v_cvt_pk_bf16_f32 v73, v78, v79
	v_cvt_pk_bf16_f32 v74, v80, v81
	v_cvt_pk_bf16_f32 v75, v82, v83
	v_cvt_pk_bf16_f32 v76, v84, v85
	v_cvt_pk_bf16_f32 v77, v86, v87
	v_cvt_pk_bf16_f32 v78, v88, v89
	v_cvt_pk_bf16_f32 v79, v90, v91
	v_cvt_pk_bf16_f32 v80, v92, v93
	v_cvt_pk_bf16_f32 v81, v94, v95
	v_cvt_pk_bf16_f32 v82, v96, v97
	v_cvt_pk_bf16_f32 v83, v98, v99
	global_store_dwordx4 v[16:17], v[68:71], off
	global_store_dwordx4 v[28:29], v[72:75], off
	global_store_dwordx4 v[26:27], v[76:79], off
	global_store_dwordx4 v[20:21], v[80:83], off
	v_lshl_add_u64 v[16:17], v[16:17], 0, s[98:99]
	v_lshl_add_u64 v[28:29], v[28:29], 0, s[98:99]
	v_lshl_add_u64 v[26:27], v[26:27], 0, s[98:99]
	v_lshl_add_u64 v[20:21], v[20:21], 0, s[98:99]
	v_lshl_add_u64 v[72:73], v[22:23], 0, v[0:1]
	v_lshl_add_u64 v[80:81], v[30:31], 0, v[0:1]
	v_lshl_add_u64 v[88:89], v[24:25], 0, v[0:1]
	v_lshl_add_u64 v[96:97], v[18:19], 0, v[0:1]
	global_load_dwordx4 v[68:71], v[72:73], off nt
	s_nop 0
	global_load_dwordx4 v[72:75], v[72:73], off offset:16 nt
	s_nop 0
	global_load_dwordx4 v[76:79], v[80:81], off offset:-16 nt
	s_nop 0
	global_load_dwordx4 v[80:83], v[80:81], off nt
	s_nop 0
	global_load_dwordx4 v[84:87], v[88:89], off offset:-16 nt
	s_nop 0
	global_load_dwordx4 v[88:91], v[88:89], off nt
	s_nop 0
	global_load_dwordx4 v[92:95], v[96:97], off offset:-16 nt
	s_nop 0
	global_load_dwordx4 v[96:99], v[96:97], off nt
	v_lshl_add_u64 v[22:23], v[22:23], 0, s[78:79]
	v_lshl_add_u64 v[30:31], v[30:31], 0, s[78:79]
	v_lshl_add_u64 v[24:25], v[24:25], 0, s[78:79]
	v_lshl_add_u64 v[18:19], v[18:19], 0, s[78:79]
	s_waitcnt vmcnt(8)
	v_cvt_pk_bf16_f32 v36, v36, v37
	v_cvt_pk_bf16_f32 v37, v38, v39
	v_cvt_pk_bf16_f32 v38, v40, v41
	v_cvt_pk_bf16_f32 v39, v42, v43
	v_cvt_pk_bf16_f32 v40, v44, v45
	v_cvt_pk_bf16_f32 v41, v46, v47
	v_cvt_pk_bf16_f32 v42, v48, v49
	v_cvt_pk_bf16_f32 v43, v50, v51
	v_cvt_pk_bf16_f32 v44, v52, v53
	v_cvt_pk_bf16_f32 v45, v54, v55
	v_cvt_pk_bf16_f32 v46, v56, v57
	v_cvt_pk_bf16_f32 v47, v58, v59
	v_cvt_pk_bf16_f32 v48, v60, v61
	v_cvt_pk_bf16_f32 v49, v62, v63
	v_cvt_pk_bf16_f32 v50, v64, v65
	v_cvt_pk_bf16_f32 v51, v66, v67
	global_store_dwordx4 v[16:17], v[36:39], off
	global_store_dwordx4 v[28:29], v[40:43], off
	global_store_dwordx4 v[26:27], v[44:47], off
	global_store_dwordx4 v[20:21], v[48:51], off
	v_lshl_add_u64 v[16:17], v[16:17], 0, s[98:99]
	v_lshl_add_u64 v[28:29], v[28:29], 0, s[98:99]
	v_lshl_add_u64 v[26:27], v[26:27], 0, s[98:99]
	v_lshl_add_u64 v[20:21], v[20:21], 0, s[98:99]
	s_sub_u32 s6, s6, 1
	s_cmp_lg_u32 s6, 0
	s_cbranch_scc1 .Lcv0_loop
	s_waitcnt vmcnt(0)
	v_cvt_pk_bf16_f32 v68, v68, v69
	v_cvt_pk_bf16_f32 v69, v70, v71
	v_cvt_pk_bf16_f32 v70, v72, v73
	v_cvt_pk_bf16_f32 v71, v74, v75
	v_cvt_pk_bf16_f32 v72, v76, v77
	v_cvt_pk_bf16_f32 v73, v78, v79
	v_cvt_pk_bf16_f32 v74, v80, v81
	v_cvt_pk_bf16_f32 v75, v82, v83
	v_cvt_pk_bf16_f32 v76, v84, v85
	v_cvt_pk_bf16_f32 v77, v86, v87
	v_cvt_pk_bf16_f32 v78, v88, v89
	v_cvt_pk_bf16_f32 v79, v90, v91
	v_cvt_pk_bf16_f32 v80, v92, v93
	v_cvt_pk_bf16_f32 v81, v94, v95
	v_cvt_pk_bf16_f32 v82, v96, v97
	v_cvt_pk_bf16_f32 v83, v98, v99
	global_store_dwordx4 v[16:17], v[68:71], off
	global_store_dwordx4 v[28:29], v[72:75], off
	global_store_dwordx4 v[26:27], v[76:79], off
	global_store_dwordx4 v[20:21], v[80:83], off
	v_lshl_add_u64 v[16:17], v[16:17], 0, s[98:99]
	v_lshl_add_u64 v[28:29], v[28:29], 0, s[98:99]
	v_lshl_add_u64 v[26:27], v[26:27], 0, s[98:99]
	v_lshl_add_u64 v[20:21], v[20:21], 0, s[98:99]
	s_mov_b64 s[6:7], 0
	s_or_b64 exec, exec, s[6:7]
	s_mov_b64 s[6:7], 0
	s_and_b64 vcc, exec, s[4:5]
	s_cbranch_vccz .LBB0_253
	s_waitcnt vmcnt(0) lgkmcnt(0)
	v_cmp_eq_u32_e32 vcc, 0, v175
	s_and_saveexec_b64 s[4:5], vcc
	s_cbranch_execz .LBB0_259
	s_mov_b64 s[6:7], exec
	v_mbcnt_lo_u32_b32 v0, s6, 0
	v_mbcnt_hi_u32_b32 v0, s7, v0
	v_cmp_eq_u32_e32 vcc, 0, v0
	s_and_b64 s[8:9], exec, vcc
	s_mov_b64 exec, s[8:9]
	s_cbranch_execz .LBB0_259
	s_bcnt1_i32_b64 s6, s[6:7]
	s_add_i32 s7, s24, 0
	s_add_i32 s7, s7, 0x20c40
	v_mov_b32_e32 v0, s7
	v_mov_b32_e32 v1, s6
	ds_add_u32 v0, v1

; __device__ __forceinline__ unsigned cvtpk(float lo, float hi) { f32x2 v = {lo, hi}; bf16x2_t b = __builtin_convertvector(v, bf16x2_t); return __builtin_bit_cast(unsigned, b); }
; template <int MODE>
; __device__ __forceinline__ void attn_unit(const UnitP& P, ALAS char* lds, const float* __restrict__ sub_gain, const int wv0, unsigned& hgen, unsigned* qctr, const int xcd) {
;     ...
;             for (int p0 = th; p0 < 16384; p0 += 1024) {
;                 f32x4 a[4], b[4];
; #pragma unroll
;                 for (int u = 0; u < 4; ++u) { const int p = p0 + 256 * u; const float* sp = src + (size_t)(p >> 4) * 1024 + (p & 15) * 8; a[u] = __builtin_nontemporal_load((const f32x4*)sp); b[u] = __builtin_nontemporal_load((const f32x4*)(sp + 4)); }
; #pragma unroll
;                 for (int u = 0; u < 4; ++u) { const int p = p0 + 256 * u;
;                     u32x4 w; w.x = cvtpk(a[u][0], a[u][1]); w.y = cvtpk(a[u][2], a[u][3]); w.z = cvtpk(b[u][0], b[u][1]); w.w = cvtpk(b[u][2], b[u][3]);
;                     *(u32x4*)(dst + (size_t)(p >> 4) * 1024 + (p & 15) * 8) = w; }
.LBB0_342:
	s_xor_b64 s[4:5], s[6:7], -1
	s_and_b64 s[6:7], s[6:7], exec
	s_cselect_b32 s6, s92, s84
	s_cselect_b32 s7, s93, s85
	s_cselect_b32 s11, s1, s87
	s_cselect_b32 s10, s0, s86
	s_add_u32 s12, s6, 16
	s_addc_u32 s13, s7, 0
	v_lshl_add_u64 v[18:19], s[10:11], 0, v[0:1]
	v_lshl_add_u64 v[20:21], s[12:13], 0, v[4:5]
	v_lshl_add_u64 v[22:23], s[10:11], 0, v[6:7]
	v_lshl_add_u64 v[24:25], s[6:7], 0, v[8:9]
	v_lshl_add_u64 v[26:27], s[12:13], 0, v[10:11]
	v_lshl_add_u64 v[28:29], s[10:11], 0, v[12:13]
	v_lshl_add_u64 v[30:31], s[10:11], 0, v[14:15]
	v_lshl_add_u64 v[32:33], s[12:13], 0, v[16:17]
	s_mov_b64 s[6:7], 0
	v_mov_b32_e32 v36, v35
	v_lshl_add_u64 v[42:43], v[24:25], 0, v[2:3]
	v_lshl_add_u64 v[50:51], v[32:33], 0, v[2:3]
	v_lshl_add_u64 v[58:59], v[26:27], 0, v[2:3]
	v_lshl_add_u64 v[66:67], v[20:21], 0, v[2:3]
	global_load_dwordx4 v[38:41], v[42:43], off nt
	s_nop 0
	global_load_dwordx4 v[42:45], v[42:43], off offset:16 nt
	s_nop 0
	global_load_dwordx4 v[46:49], v[50:51], off offset:-16 nt
	s_nop 0
	global_load_dwordx4 v[50:53], v[50:51], off nt
	s_nop 0
	global_load_dwordx4 v[54:57], v[58:59], off offset:-16 nt
	s_nop 0
	global_load_dwordx4 v[58:61], v[58:59], off nt
	s_nop 0
	global_load_dwordx4 v[62:65], v[66:67], off offset:-16 nt
	s_nop 0
	global_load_dwordx4 v[66:69], v[66:67], off nt
	v_lshl_add_u64 v[24:25], v[24:25], 0, s[78:79]
	v_lshl_add_u64 v[32:33], v[32:33], 0, s[78:79]
	v_lshl_add_u64 v[26:27], v[26:27], 0, s[78:79]
	v_lshl_add_u64 v[20:21], v[20:21], 0, s[78:79]
	v_lshl_add_u64 v[74:75], v[24:25], 0, v[2:3]
	v_lshl_add_u64 v[82:83], v[32:33], 0, v[2:3]
	v_lshl_add_u64 v[90:91], v[26:27], 0, v[2:3]
	v_lshl_add_u64 v[98:99], v[20:21], 0, v[2:3]
	global_load_dwordx4 v[70:73], v[74:75], off nt
	s_nop 0
	global_load_dwordx4 v[74:77], v[74:75], off offset:16 nt
	s_nop 0
	global_load_dwordx4 v[78:81], v[82:83], off offset:-16 nt
	s_nop 0
	global_load_dwordx4 v[82:85], v[82:83], off nt
	s_nop 0
	global_load_dwordx4 v[86:89], v[90:91], off offset:-16 nt
	s_nop 0
	global_load_dwordx4 v[90:93], v[90:91], off nt
	s_nop 0
	global_load_dwordx4 v[94:97], v[98:99], off offset:-16 nt
	s_nop 0
	global_load_dwordx4 v[98:101], v[98:99], off nt
	v_lshl_add_u64 v[24:25], v[24:25], 0, s[78:79]
	v_lshl_add_u64 v[32:33], v[32:33], 0, s[78:79]
	v_lshl_add_u64 v[26:27], v[26:27], 0, s[78:79]
	v_lshl_add_u64 v[20:21], v[20:21], 0, s[78:79]
	s_waitcnt vmcnt(8)
	v_cvt_pk_bf16_f32 v38, v38, v39
	v_cvt_pk_bf16_f32 v39, v40, v41
	v_cvt_pk_bf16_f32 v40, v42, v43
	v_cvt_pk_bf16_f32 v41, v44, v45
	v_cvt_pk_bf16_f32 v42, v46, v47
	v_cvt_pk_bf16_f32 v43, v48, v49
	v_cvt_pk_bf16_f32 v44, v50, v51
	v_cvt_pk_bf16_f32 v45, v52, v53
	v_cvt_pk_bf16_f32 v46, v54, v55
	v_cvt_pk_bf16_f32 v47, v56, v57
	v_cvt_pk_bf16_f32 v48, v58, v59
	v_cvt_pk_bf16_f32 v49, v60, v61
	v_cvt_pk_bf16_f32 v50, v62, v63
	v_cvt_pk_bf16_f32 v51, v64, v65
	v_cvt_pk_bf16_f32 v52, v66, v67
	v_cvt_pk_bf16_f32 v53, v68, v69
	global_store_dwordx4 v[18:19], v[38:41], off
	global_store_dwordx4 v[30:31], v[42:45], off
	global_store_dwordx4 v[28:29], v[46:49], off
	global_store_dwordx4 v[22:23], v[50:53], off
	v_lshl_add_u64 v[18:19], v[18:19], 0, s[98:99]
	v_lshl_add_u64 v[30:31], v[30:31], 0, s[98:99]
	v_lshl_add_u64 v[28:29], v[28:29], 0, s[98:99]
	v_lshl_add_u64 v[22:23], v[22:23], 0, s[98:99]
	s_mov_b32 s6, 7
; __device__ __forceinline__ unsigned cvtpk(float lo, float hi) { f32x2 v = {lo, hi}; bf16x2_t b = __builtin_convertvector(v, bf16x2_t); return __builtin_bit_cast(unsigned, b); }
; template <int MODE>
; __device__ __forceinline__ void attn_unit(const UnitP& P, ALAS char* lds, const float* __restrict__ sub_gain, const int wv0, unsigned& hgen, unsigned* qctr, const int xcd) {
;     ...
;             for (int p0 = th; p0 < 16384; p0 += 1024) {
;                 f32x4 a[4], b[4];
; #pragma unroll
;                 for (int u = 0; u < 4; ++u) { const int p = p0 + 256 * u; const float* sp = src + (size_t)(p >> 4) * 1024 + (p & 15) * 8; a[u] = __builtin_nontemporal_load((const f32x4*)sp); b[u] = __builtin_nontemporal_load((const f32x4*)(sp + 4)); }
; #pragma unroll
;                 for (int u = 0; u < 4; ++u) { const int p = p0 + 256 * u;
;                     u32x4 w; w.x = cvtpk(a[u][0], a[u][1]); w.y = cvtpk(a[u][2], a[u][3]); w.z = cvtpk(b[u][0], b[u][1]); w.w = cvtpk(b[u][2], b[u][3]);
;                     *(u32x4*)(dst + (size_t)(p >> 4) * 1024 + (p & 15) * 8) = w; }
.Lcv1_loop:
	v_lshl_add_u64 v[42:43], v[24:25], 0, v[2:3]
	v_lshl_add_u64 v[50:51], v[32:33], 0, v[2:3]
	v_lshl_add_u64 v[58:59], v[26:27], 0, v[2:3]
	v_lshl_add_u64 v[66:67], v[20:21], 0, v[2:3]
	global_load_dwordx4 v[38:41], v[42:43], off nt
	s_nop 0
	global_load_dwordx4 v[42:45], v[42:43], off offset:16 nt
	s_nop 0
	global_load_dwordx4 v[46:49], v[50:51], off offset:-16 nt
	s_nop 0
	global_load_dwordx4 v[50:53], v[50:51], off nt
	s_nop 0
	global_load_dwordx4 v[54:57], v[58:59], off offset:-16 nt
	s_nop 0
	global_load_dwordx4 v[58:61], v[58:59], off nt
	s_nop 0
	global_load_dwordx4 v[62:65], v[66:67], off offset:-16 nt
	s_nop 0
	global_load_dwordx4 v[66:69], v[66:67], off nt
	v_lshl_add_u64 v[24:25], v[24:25], 0, s[78:79]
	v_lshl_add_u64 v[32:33], v[32:33], 0, s[78:79]
	v_lshl_add_u64 v[26:27], v[26:27], 0, s[78:79]
	v_lshl_add_u64 v[20:21], v[20:21], 0, s[78:79]
	s_waitcnt vmcnt(8)
	v_cvt_pk_bf16_f32 v70, v70, v71
	v_cvt_pk_bf16_f32 v71, v72, v73
	v_cvt_pk_bf16_f32 v72, v74, v75
	v_cvt_pk_bf16_f32 v73, v76, v77
	v_cvt_pk_bf16_f32 v74, v78, v79
	v_cvt_pk_bf16_f32 v75, v80, v81
	v_cvt_pk_bf16_f32 v76, v82, v83
	v_cvt_pk_bf16_f32 v77, v84, v85
	v_cvt_pk_bf16_f32 v78, v86, v87
	v_cvt_pk_bf16_f32 v79, v88, v89
	v_cvt_pk_bf16_f32 v80, v90, v91
	v_cvt_pk_bf16_f32 v81, v92, v93
	v_cvt_pk_bf16_f32 v82, v94, v95
	v_cvt_pk_bf16_f32 v83, v96, v97
	v_cvt_pk_bf16_f32 v84, v98, v99
	v_cvt_pk_bf16_f32 v85, v100, v101
	global_store_dwordx4 v[18:19], v[70:73], off
	global_store_dwordx4 v[30:31], v[74:77], off
	global_store_dwordx4 v[28:29], v[78:81], off
	global_store_dwordx4 v[22:23], v[82:85], off
	v_lshl_add_u64 v[18:19], v[18:19], 0, s[98:99]
	v_lshl_add_u64 v[30:31], v[30:31], 0, s[98:99]
	v_lshl_add_u64 v[28:29], v[28:29], 0, s[98:99]
	v_lshl_add_u64 v[22:23], v[22:23], 0, s[98:99]
	v_lshl_add_u64 v[74:75], v[24:25], 0, v[2:3]
	v_lshl_add_u64 v[82:83], v[32:33], 0, v[2:3]
	v_lshl_add_u64 v[90:91], v[26:27], 0, v[2:3]
	v_lshl_add_u64 v[98:99], v[20:21], 0, v[2:3]
	global_load_dwordx4 v[70:73], v[74:75], off nt
	s_nop 0
	global_load_dwordx4 v[74:77], v[74:75], off offset:16 nt
	s_nop 0
	global_load_dwordx4 v[78:81], v[82:83], off offset:-16 nt
	s_nop 0
	global_load_dwordx4 v[82:85], v[82:83], off nt
	s_nop 0
	global_load_dwordx4 v[86:89], v[90:91], off offset:-16 nt
	s_nop 0
	global_load_dwordx4 v[90:93], v[90:91], off nt
	s_nop 0
	global_load_dwordx4 v[94:97], v[98:99], off offset:-16 nt
	s_nop 0
	global_load_dwordx4 v[98:101], v[98:99], off nt
	v_lshl_add_u64 v[24:25], v[24:25], 0, s[78:79]
	v_lshl_add_u64 v[32:33], v[32:33], 0, s[78:79]
	v_lshl_add_u64 v[26:27], v[26:27], 0, s[78:79]
	v_lshl_add_u64 v[20:21], v[20:21], 0, s[78:79]
	s_waitcnt vmcnt(8)
	v_cvt_pk_bf16_f32 v38, v38, v39
	v_cvt_pk_bf16_f32 v39, v40, v41
	v_cvt_pk_bf16_f32 v40, v42, v43
	v_cvt_pk_bf16_f32 v41, v44, v45
	v_cvt_pk_bf16_f32 v42, v46, v47
	v_cvt_pk_bf16_f32 v43, v48, v49
	v_cvt_pk_bf16_f32 v44, v50, v51
	v_cvt_pk_bf16_f32 v45, v52, v53
	v_cvt_pk_bf16_f32 v46, v54, v55
	v_cvt_pk_bf16_f32 v47, v56, v57
	v_cvt_pk_bf16_f32 v48, v58, v59
	v_cvt_pk_bf16_f32 v49, v60, v61
	v_cvt_pk_bf16_f32 v50, v62, v63
	v_cvt_pk_bf16_f32 v51, v64, v65
	v_cvt_pk_bf16_f32 v52, v66, v67
	v_cvt_pk_bf16_f32 v53, v68, v69
	global_store_dwordx4 v[18:19], v[38:41], off
	global_store_dwordx4 v[30:31], v[42:45], off
	global_store_dwordx4 v[28:29], v[46:49], off
	global_store_dwordx4 v[22:23], v[50:53], off
	v_lshl_add_u64 v[18:19], v[18:19], 0, s[98:99]
	v_lshl_add_u64 v[30:31], v[30:31], 0, s[98:99]
	v_lshl_add_u64 v[28:29], v[28:29], 0, s[98:99]
	v_lshl_add_u64 v[22:23], v[22:23], 0, s[98:99]
	s_sub_u32 s6, s6, 1
	s_cmp_lg_u32 s6, 0
	s_cbranch_scc1 .Lcv1_loop
	s_waitcnt vmcnt(0)
	v_cvt_pk_bf16_f32 v70, v70, v71
	v_cvt_pk_bf16_f32 v71, v72, v73
	v_cvt_pk_bf16_f32 v72, v74, v75
	v_cvt_pk_bf16_f32 v73, v76, v77
	v_cvt_pk_bf16_f32 v74, v78, v79
	v_cvt_pk_bf16_f32 v75, v80, v81
	v_cvt_pk_bf16_f32 v76, v82, v83
	v_cvt_pk_bf16_f32 v77, v84, v85
	v_cvt_pk_bf16_f32 v78, v86, v87
	v_cvt_pk_bf16_f32 v79, v88, v89
	v_cvt_pk_bf16_f32 v80, v90, v91
	v_cvt_pk_bf16_f32 v81, v92, v93
	v_cvt_pk_bf16_f32 v82, v94, v95
	v_cvt_pk_bf16_f32 v83, v96, v97
	v_cvt_pk_bf16_f32 v84, v98, v99
	v_cvt_pk_bf16_f32 v85, v100, v101
	global_store_dwordx4 v[18:19], v[70:73], off
	global_store_dwordx4 v[30:31], v[74:77], off
	global_store_dwordx4 v[28:29], v[78:81], off
	global_store_dwordx4 v[22:23], v[82:85], off
	v_lshl_add_u64 v[18:19], v[18:19], 0, s[98:99]
	v_lshl_add_u64 v[30:31], v[30:31], 0, s[98:99]
	v_lshl_add_u64 v[28:29], v[28:29], 0, s[98:99]
	v_lshl_add_u64 v[22:23], v[22:23], 0, s[98:99]
	s_mov_b64 s[6:7], 0
	s_or_b64 exec, exec, s[6:7]
	s_mov_b64 s[6:7], 0
	s_and_b64 vcc, exec, s[4:5]
	s_cbranch_vccz .LBB0_342
	s_waitcnt vmcnt(0) lgkmcnt(0)
	v_cmp_eq_u32_e32 vcc, 0, v176
	s_and_saveexec_b64 s[4:5], vcc
	s_cbranch_execz .LBB0_348
	s_mov_b64 s[6:7], exec
	v_mbcnt_lo_u32_b32 v0, s6, 0
	v_mbcnt_hi_u32_b32 v0, s7, v0
	v_cmp_eq_u32_e32 vcc, 0, v0
	s_and_b64 s[10:11], exec, vcc
	s_mov_b64 exec, s[10:11]
	s_cbranch_execz .LBB0_348
	s_bcnt1_i32_b64 s6, s[6:7]
	s_add_i32 s7, s22, 0
	s_add_i32 s7, s7, 0x20c40
	v_mov_b32_e32 v0, s7
	v_mov_b32_e32 v1, s6
	ds_add_u32 v0, v1

; __device__ __forceinline__ float sum32(float v) { auto rr = __builtin_amdgcn_permlane32_swap(__float_as_uint(v), __float_as_uint(v), false, false); return __uint_as_float(rr[0]) + __uint_as_float(rr[1]); }
;     __device__ __forceinline__ void operator()(const f32x4 (&acc)[2][2][4][2], const Unit& u, int wr, int wc, int fr, int fq) const {
;         const int row0 = u.pm * BM + wr * 64 + fr, col0 = u.pn * BM + wc * 32 + 4 * fq;
;         const float* xb = u.pm >= 128 ? xs - (size_t)32768 * 2048 : xp;
; #pragma unroll
;         for (int ai = 0; ai < 2; ++ai)
; #pragma unroll
;             for (int m = 0; m < 4; ++m) {
;                 const int row = row0 + ai * HALF + m * 16; const size_t off = (size_t)row * 2048 + col0; float ss = 0.f;
; #pragma unroll
;                 for (int bj = 0; bj < 2; ++bj)
; #pragma unroll
;                     for (int n = 0; n < 2; ++n) { const f32x4 xv = *(const f32x4*)(xb + off + bj * HALF + n * 16); const f32x4 hv = xv + acc[ai][bj][m][n];
;                         *(f32x4*)(out + off + bj * HALF + n * 16) = hv; ss += (hv[0] * hv[0] + hv[1] * hv[1]) + (hv[2] * hv[2] + hv[3] * hv[3]); }
;                 ss += shx<16>(ss); ss = sum32(ss);
;                 if (fq == 0) atomicAdd(sumsq + row, ss);
.LBB0_439:
	v_lshl_add_u32 v142, s22, 8, v144
	v_lshl_or_b32 v140, s20, 8, v146
	v_ashrrev_i32_e32 v143, 31, v142
	s_cmpk_gt_i32 s22, 0x7f
	v_readlane_b32 s20, v252, 3
	v_ashrrev_i32_e32 v141, 31, v140
	v_lshlrev_b64 v[150:151], 11, v[142:143]
	v_readlane_b32 s21, v252, 4
	v_lshl_add_u64 v[150:151], v[150:151], 0, v[140:141]
	s_cselect_b32 s21, s40, s21
	s_cselect_b32 s20, s39, s20
	v_lshlrev_b64 v[154:155], 2, v[150:151]
	v_lshl_add_u64 v[156:157], s[20:21], 0, v[154:155]
	v_lshl_add_u64 v[154:155], s[54:55], 0, v[154:155]
	v_readlane_b32 s22, v252, 5
	v_readlane_b32 s23, v252, 6
	v_lshl_add_u64 v[206:207], v[142:143], 2, s[6:7]
	global_load_dwordx4 v[158:161], v[156:157], off
	global_load_dwordx4 v[162:165], v[156:157], off offset:64
	global_load_dwordx4 v[166:169], v[156:157], off offset:512
	global_load_dwordx4 v[170:173], v[156:157], off offset:576
	s_mov_b64 vcc, 0x20000
	v_lshl_add_u64 v[156:157], v[156:157], 0, vcc
	global_load_dwordx4 v[174:177], v[156:157], off
	global_load_dwordx4 v[178:181], v[156:157], off offset:64
	global_load_dwordx4 v[182:185], v[156:157], off offset:512
	global_load_dwordx4 v[186:189], v[156:157], off offset:576
	s_mov_b64 vcc, 0x20000
	v_lshl_add_u64 v[156:157], v[156:157], 0, vcc
	global_load_dwordx4 v[190:193], v[156:157], off
	global_load_dwordx4 v[194:197], v[156:157], off offset:64
	global_load_dwordx4 v[198:201], v[156:157], off offset:512
	global_load_dwordx4 v[202:205], v[156:157], off offset:576
	s_mov_b64 vcc, 0x20000
	v_lshl_add_u64 v[156:157], v[156:157], 0, vcc
	s_waitcnt vmcnt(8)
	v_pk_add_f32 v[126:127], v[126:127], v[160:161]
	v_pk_add_f32 v[124:125], v[124:125], v[158:159]
	global_store_dwordx4 v[154:155], v[124:127], off
	v_pk_add_f32 v[122:123], v[122:123], v[164:165]
	v_pk_add_f32 v[120:121], v[120:121], v[162:163]
	global_store_dwordx4 v[154:155], v[120:123], off offset:64
	v_pk_add_f32 v[118:119], v[118:119], v[168:169]
	v_pk_add_f32 v[116:117], v[116:117], v[166:167]
	global_store_dwordx4 v[154:155], v[116:119], off offset:512
	v_pk_add_f32 v[114:115], v[114:115], v[172:173]
	v_pk_add_f32 v[112:113], v[112:113], v[170:171]
	global_store_dwordx4 v[154:155], v[112:115], off offset:576
	v_mul_f32_e32 v208, v125, v125
	v_mul_f32_e32 v209, v127, v127
	v_fmac_f32_e32 v208, v124, v124
	v_fmac_f32_e32 v209, v126, v126
	v_add_f32_e32 v211, v208, v209
	v_mul_f32_e32 v208, v121, v121
	v_mul_f32_e32 v209, v123, v123
	v_fmac_f32_e32 v208, v120, v120
	v_fmac_f32_e32 v209, v122, v122
	v_add_f32_e32 v210, v208, v209
	v_add_f32_e32 v211, v211, v210
	v_mul_f32_e32 v208, v117, v117
	v_mul_f32_e32 v209, v119, v119
	v_fmac_f32_e32 v208, v116, v116
	v_fmac_f32_e32 v209, v118, v118
	v_add_f32_e32 v210, v208, v209
	v_add_f32_e32 v211, v211, v210
	v_mul_f32_e32 v208, v113, v113
	v_mul_f32_e32 v209, v115, v115
	v_fmac_f32_e32 v208, v112, v112
	v_fmac_f32_e32 v209, v114, v114
	v_add_f32_e32 v210, v208, v209
	v_add_f32_e32 v211, v211, v210
	ds_swizzle_b32 v212, v211 offset:swizzle(SWAP,16)
	s_mov_b64 vcc, 0x20000
	v_lshl_add_u64 v[154:155], v[154:155], 0, vcc
	s_waitcnt lgkmcnt(0)
	s_nop 0
	v_add_f32_e32 v211, v211, v212
	v_mov_b32_e32 v213, v211
	s_nop 1
	v_permlane32_swap_b32_e32 v211, v213
	s_and_saveexec_b64 s[22:23], s[0:1]
	s_cbranch_execz .Lp3e_0
	v_add_f32_e32 v211, v211, v213
	global_atomic_add_f32 v[206:207], v211, off
.Lp3e_0:
	s_or_b64 exec, exec, s[22:23]
	global_load_dwordx4 v[158:161], v[156:157], off
	global_load_dwordx4 v[162:165], v[156:157], off offset:64
	global_load_dwordx4 v[166:169], v[156:157], off offset:512
	global_load_dwordx4 v[170:173], v[156:157], off offset:576
	s_mov_b64 vcc, 0xa0000
	v_lshl_add_u64 v[156:157], v[156:157], 0, vcc
	s_waitcnt vmcnt(12)
	v_pk_add_f32 v[110:111], v[110:111], v[176:177]
	v_pk_add_f32 v[108:109], v[108:109], v[174:175]
	global_store_dwordx4 v[154:155], v[108:111], off
	v_pk_add_f32 v[106:107], v[106:107], v[180:181]
	v_pk_add_f32 v[104:105], v[104:105], v[178:179]
	global_store_dwordx4 v[154:155], v[104:107], off offset:64
	v_pk_add_f32 v[102:103], v[102:103], v[184:185]
	v_pk_add_f32 v[100:101], v[100:101], v[182:183]
	global_store_dwordx4 v[154:155], v[100:103], off offset:512
	v_pk_add_f32 v[98:99], v[98:99], v[188:189]
	v_pk_add_f32 v[96:97], v[96:97], v[186:187]
	global_store_dwordx4 v[154:155], v[96:99], off offset:576
	v_mul_f32_e32 v208, v109, v109
	v_mul_f32_e32 v209, v111, v111
	v_fmac_f32_e32 v208, v108, v108
	v_fmac_f32_e32 v209, v110, v110
	v_add_f32_e32 v211, v208, v209
	v_mul_f32_e32 v208, v105, v105
	v_mul_f32_e32 v209, v107, v107
	v_fmac_f32_e32 v208, v104, v104
	v_fmac_f32_e32 v209, v106, v106
	v_add_f32_e32 v210, v208, v209
	v_add_f32_e32 v211, v211, v210
	v_mul_f32_e32 v208, v101, v101
	v_mul_f32_e32 v209, v103, v103
	v_fmac_f32_e32 v208, v100, v100
	v_fmac_f32_e32 v209, v102, v102
	v_add_f32_e32 v210, v208, v209
	v_add_f32_e32 v211, v211, v210
	v_mul_f32_e32 v208, v97, v97
	v_mul_f32_e32 v209, v99, v99
	v_fmac_f32_e32 v208, v96, v96
	v_fmac_f32_e32 v209, v98, v98
	v_add_f32_e32 v210, v208, v209
	v_add_f32_e32 v211, v211, v210
	ds_swizzle_b32 v212, v211 offset:swizzle(SWAP,16)
	s_mov_b64 vcc, 0x20000
	v_lshl_add_u64 v[154:155], v[154:155], 0, vcc
	s_waitcnt lgkmcnt(0)
	s_nop 0
	v_add_f32_e32 v211, v211, v212
	v_mov_b32_e32 v213, v211
	s_nop 1
	v_permlane32_swap_b32_e32 v211, v213
	s_and_saveexec_b64 s[22:23], s[0:1]
	s_cbranch_execz .Lp3e_1
	v_add_f32_e32 v211, v211, v213
	global_atomic_add_f32 v[206:207], v211, off offset:64
; __device__ __forceinline__ float sum32(float v) { auto rr = __builtin_amdgcn_permlane32_swap(__float_as_uint(v), __float_as_uint(v), false, false); return __uint_as_float(rr[0]) + __uint_as_float(rr[1]); }
;     __device__ __forceinline__ void operator()(const f32x4 (&acc)[2][2][4][2], const Unit& u, int wr, int wc, int fr, int fq) const {
;     ...
;             for (int m = 0; m < 4; ++m) {
;                 const int row = row0 + ai * HALF + m * 16; const size_t off = (size_t)row * 2048 + col0; float ss = 0.f;
; #pragma unroll
;                 for (int bj = 0; bj < 2; ++bj)
; #pragma unroll
;                     for (int n = 0; n < 2; ++n) { const f32x4 xv = *(const f32x4*)(xb + off + bj * HALF + n * 16); const f32x4 hv = xv + acc[ai][bj][m][n];
;                         *(f32x4*)(out + off + bj * HALF + n * 16) = hv; ss += (hv[0] * hv[0] + hv[1] * hv[1]) + (hv[2] * hv[2] + hv[3] * hv[3]); }
;                 ss += shx<16>(ss); ss = sum32(ss);
;                 if (fq == 0) atomicAdd(sumsq + row, ss);
.Lp3e_1:
	s_or_b64 exec, exec, s[22:23]
	global_load_dwordx4 v[174:177], v[156:157], off
	global_load_dwordx4 v[178:181], v[156:157], off offset:64
	global_load_dwordx4 v[182:185], v[156:157], off offset:512
	global_load_dwordx4 v[186:189], v[156:157], off offset:576
	s_mov_b64 vcc, 0x20000
	v_lshl_add_u64 v[156:157], v[156:157], 0, vcc
	s_waitcnt vmcnt(16)
	v_pk_add_f32 v[94:95], v[94:95], v[192:193]
	v_pk_add_f32 v[92:93], v[92:93], v[190:191]
	global_store_dwordx4 v[154:155], v[92:95], off
	v_pk_add_f32 v[90:91], v[90:91], v[196:197]
	v_pk_add_f32 v[88:89], v[88:89], v[194:195]
	global_store_dwordx4 v[154:155], v[88:91], off offset:64
	v_pk_add_f32 v[86:87], v[86:87], v[200:201]
	v_pk_add_f32 v[84:85], v[84:85], v[198:199]
	global_store_dwordx4 v[154:155], v[84:87], off offset:512
	v_pk_add_f32 v[82:83], v[82:83], v[204:205]
	v_pk_add_f32 v[80:81], v[80:81], v[202:203]
	global_store_dwordx4 v[154:155], v[80:83], off offset:576
	v_mul_f32_e32 v208, v93, v93
	v_mul_f32_e32 v209, v95, v95
	v_fmac_f32_e32 v208, v92, v92
	v_fmac_f32_e32 v209, v94, v94
	v_add_f32_e32 v211, v208, v209
	v_mul_f32_e32 v208, v89, v89
	v_mul_f32_e32 v209, v91, v91
	v_fmac_f32_e32 v208, v88, v88
	v_fmac_f32_e32 v209, v90, v90
	v_add_f32_e32 v210, v208, v209
	v_add_f32_e32 v211, v211, v210
	v_mul_f32_e32 v208, v85, v85
	v_mul_f32_e32 v209, v87, v87
	v_fmac_f32_e32 v208, v84, v84
	v_fmac_f32_e32 v209, v86, v86
	v_add_f32_e32 v210, v208, v209
	v_add_f32_e32 v211, v211, v210
	v_mul_f32_e32 v208, v81, v81
	v_mul_f32_e32 v209, v83, v83
	v_fmac_f32_e32 v208, v80, v80
	v_fmac_f32_e32 v209, v82, v82
	v_add_f32_e32 v210, v208, v209
	v_add_f32_e32 v211, v211, v210
	ds_swizzle_b32 v212, v211 offset:swizzle(SWAP,16)
	s_mov_b64 vcc, 0x20000
	v_lshl_add_u64 v[154:155], v[154:155], 0, vcc
	s_waitcnt lgkmcnt(0)
	s_nop 0
	v_add_f32_e32 v211, v211, v212
	v_mov_b32_e32 v213, v211
	s_nop 1
	v_permlane32_swap_b32_e32 v211, v213
	s_and_saveexec_b64 s[22:23], s[0:1]
	s_cbranch_execz .Lp3e_2
	v_add_f32_e32 v211, v211, v213
	global_atomic_add_f32 v[206:207], v211, off offset:128
.Lp3e_2:
	s_or_b64 exec, exec, s[22:23]
	global_load_dwordx4 v[190:193], v[156:157], off
	global_load_dwordx4 v[194:197], v[156:157], off offset:64
	global_load_dwordx4 v[198:201], v[156:157], off offset:512
	global_load_dwordx4 v[202:205], v[156:157], off offset:576
	s_mov_b64 vcc, 0x20000
	v_lshl_add_u64 v[156:157], v[156:157], 0, vcc
	s_waitcnt vmcnt(16)
	v_pk_add_f32 v[78:79], v[78:79], v[160:161]
	v_pk_add_f32 v[76:77], v[76:77], v[158:159]
	global_store_dwordx4 v[154:155], v[76:79], off
	v_pk_add_f32 v[74:75], v[74:75], v[164:165]
	v_pk_add_f32 v[72:73], v[72:73], v[162:163]
	global_store_dwordx4 v[154:155], v[72:75], off offset:64
	v_pk_add_f32 v[70:71], v[70:71], v[168:169]
	v_pk_add_f32 v[68:69], v[68:69], v[166:167]
	global_store_dwordx4 v[154:155], v[68:71], off offset:512
	v_pk_add_f32 v[66:67], v[66:67], v[172:173]
	v_pk_add_f32 v[64:65], v[64:65], v[170:171]
	global_store_dwordx4 v[154:155], v[64:67], off offset:576
	v_mul_f32_e32 v208, v77, v77
	v_mul_f32_e32 v209, v79, v79
	v_fmac_f32_e32 v208, v76, v76
	v_fmac_f32_e32 v209, v78, v78
	v_add_f32_e32 v211, v208, v209
	v_mul_f32_e32 v208, v73, v73
	v_mul_f32_e32 v209, v75, v75
	v_fmac_f32_e32 v208, v72, v72
	v_fmac_f32_e32 v209, v74, v74
	v_add_f32_e32 v210, v208, v209
	v_add_f32_e32 v211, v211, v210
	v_mul_f32_e32 v208, v69, v69
	v_mul_f32_e32 v209, v71, v71
	v_fmac_f32_e32 v208, v68, v68
	v_fmac_f32_e32 v209, v70, v70
	v_add_f32_e32 v210, v208, v209
	v_add_f32_e32 v211, v211, v210
	v_mul_f32_e32 v208, v65, v65
	v_mul_f32_e32 v209, v67, v67
	v_fmac_f32_e32 v208, v64, v64
	v_fmac_f32_e32 v209, v66, v66
	v_add_f32_e32 v210, v208, v209
	v_add_f32_e32 v211, v211, v210
	ds_swizzle_b32 v212, v211 offset:swizzle(SWAP,16)
	s_mov_b64 vcc, 0xa0000
	v_lshl_add_u64 v[154:155], v[154:155], 0, vcc
	s_waitcnt lgkmcnt(0)
	s_nop 0
	v_add_f32_e32 v211, v211, v212
	v_mov_b32_e32 v213, v211
	s_nop 1
	v_permlane32_swap_b32_e32 v211, v213
	s_and_saveexec_b64 s[22:23], s[0:1]
	s_cbranch_execz .Lp3e_3
	v_add_f32_e32 v211, v211, v213
	global_atomic_add_f32 v[206:207], v211, off offset:192
.Lp3e_3:
	s_or_b64 exec, exec, s[22:23]
	global_load_dwordx4 v[158:161], v[156:157], off
	global_load_dwordx4 v[162:165], v[156:157], off offset:64
	global_load_dwordx4 v[166:169], v[156:157], off offset:512
	global_load_dwordx4 v[170:173], v[156:157], off offset:576
	s_mov_b64 vcc, 0x20000
	v_lshl_add_u64 v[156:157], v[156:157], 0, vcc
	s_waitcnt vmcnt(16)
	v_pk_add_f32 v[62:63], v[62:63], v[176:177]
	v_pk_add_f32 v[60:61], v[60:61], v[174:175]
	global_store_dwordx4 v[154:155], v[60:63], off
	v_pk_add_f32 v[58:59], v[58:59], v[180:181]
	v_pk_add_f32 v[56:57], v[56:57], v[178:179]
	global_store_dwordx4 v[154:155], v[56:59], off offset:64
	v_pk_add_f32 v[54:55], v[54:55], v[184:185]
	v_pk_add_f32 v[52:53], v[52:53], v[182:183]
	global_store_dwordx4 v[154:155], v[52:55], off offset:512
	v_pk_add_f32 v[50:51], v[50:51], v[188:189]
	v_pk_add_f32 v[48:49], v[48:49], v[186:187]
	global_store_dwordx4 v[154:155], v[48:51], off offset:576
	v_mul_f32_e32 v208, v61, v61
	v_mul_f32_e32 v209, v63, v63
	v_fmac_f32_e32 v208, v60, v60
	v_fmac_f32_e32 v209, v62, v62
	v_add_f32_e32 v211, v208, v209
	v_mul_f32_e32 v208, v57, v57
	v_mul_f32_e32 v209, v59, v59
	v_fmac_f32_e32 v208, v56, v56
	v_fmac_f32_e32 v209, v58, v58
	v_add_f32_e32 v210, v208, v209
	v_add_f32_e32 v211, v211, v210
	v_mul_f32_e32 v208, v53, v53
	v_mul_f32_e32 v209, v55, v55
	v_fmac_f32_e32 v208, v52, v52
	v_fmac_f32_e32 v209, v54, v54
	v_add_f32_e32 v210, v208, v209
	v_add_f32_e32 v211, v211, v210
	v_mul_f32_e32 v208, v49, v49
	v_mul_f32_e32 v209, v51, v51
	v_fmac_f32_e32 v208, v48, v48
	v_fmac_f32_e32 v209, v50, v50
	v_add_f32_e32 v210, v208, v209
	v_add_f32_e32 v211, v211, v210
	ds_swizzle_b32 v212, v211 offset:swizzle(SWAP,16)
	s_mov_b64 vcc, 0x20000
	v_lshl_add_u64 v[154:155], v[154:155], 0, vcc
	s_waitcnt lgkmcnt(0)
	s_nop 0
	v_add_f32_e32 v211, v211, v212
	v_mov_b32_e32 v213, v211
	s_nop 1
	v_permlane32_swap_b32_e32 v211, v213
	s_and_saveexec_b64 s[22:23], s[0:1]
	s_cbranch_execz .Lp3e_4
	v_add_f32_e32 v211, v211, v213
	global_atomic_add_f32 v[206:207], v211, off offset:512
; __device__ __forceinline__ float sum32(float v) { auto rr = __builtin_amdgcn_permlane32_swap(__float_as_uint(v), __float_as_uint(v), false, false); return __uint_as_float(rr[0]) + __uint_as_float(rr[1]); }
;     __device__ __forceinline__ void operator()(const f32x4 (&acc)[2][2][4][2], const Unit& u, int wr, int wc, int fr, int fq) const {
;     ...
;             for (int m = 0; m < 4; ++m) {
;                 const int row = row0 + ai * HALF + m * 16; const size_t off = (size_t)row * 2048 + col0; float ss = 0.f;
; #pragma unroll
;                 for (int bj = 0; bj < 2; ++bj)
; #pragma unroll
;                     for (int n = 0; n < 2; ++n) { const f32x4 xv = *(const f32x4*)(xb + off + bj * HALF + n * 16); const f32x4 hv = xv + acc[ai][bj][m][n];
;                         *(f32x4*)(out + off + bj * HALF + n * 16) = hv; ss += (hv[0] * hv[0] + hv[1] * hv[1]) + (hv[2] * hv[2] + hv[3] * hv[3]); }
;                 ss += shx<16>(ss); ss = sum32(ss);
;                 if (fq == 0) atomicAdd(sumsq + row, ss);
.Lp3e_4:
	s_or_b64 exec, exec, s[22:23]
	global_load_dwordx4 v[174:177], v[156:157], off
	global_load_dwordx4 v[178:181], v[156:157], off offset:64
	global_load_dwordx4 v[182:185], v[156:157], off offset:512
	global_load_dwordx4 v[186:189], v[156:157], off offset:576
	s_waitcnt vmcnt(16)
	v_pk_add_f32 v[46:47], v[46:47], v[192:193]
	v_pk_add_f32 v[44:45], v[44:45], v[190:191]
	global_store_dwordx4 v[154:155], v[44:47], off
	v_pk_add_f32 v[42:43], v[42:43], v[196:197]
	v_pk_add_f32 v[40:41], v[40:41], v[194:195]
	global_store_dwordx4 v[154:155], v[40:43], off offset:64
	v_pk_add_f32 v[38:39], v[38:39], v[200:201]
	v_pk_add_f32 v[36:37], v[36:37], v[198:199]
	global_store_dwordx4 v[154:155], v[36:39], off offset:512
	v_pk_add_f32 v[34:35], v[34:35], v[204:205]
	v_pk_add_f32 v[32:33], v[32:33], v[202:203]
	global_store_dwordx4 v[154:155], v[32:35], off offset:576
	v_mul_f32_e32 v208, v45, v45
	v_mul_f32_e32 v209, v47, v47
	v_fmac_f32_e32 v208, v44, v44
	v_fmac_f32_e32 v209, v46, v46
	v_add_f32_e32 v211, v208, v209
	v_mul_f32_e32 v208, v41, v41
	v_mul_f32_e32 v209, v43, v43
	v_fmac_f32_e32 v208, v40, v40
	v_fmac_f32_e32 v209, v42, v42
	v_add_f32_e32 v210, v208, v209
	v_add_f32_e32 v211, v211, v210
	v_mul_f32_e32 v208, v37, v37
	v_mul_f32_e32 v209, v39, v39
	v_fmac_f32_e32 v208, v36, v36
	v_fmac_f32_e32 v209, v38, v38
	v_add_f32_e32 v210, v208, v209
	v_add_f32_e32 v211, v211, v210
	v_mul_f32_e32 v208, v33, v33
	v_mul_f32_e32 v209, v35, v35
	v_fmac_f32_e32 v208, v32, v32
	v_fmac_f32_e32 v209, v34, v34
	v_add_f32_e32 v210, v208, v209
	v_add_f32_e32 v211, v211, v210
	ds_swizzle_b32 v212, v211 offset:swizzle(SWAP,16)
	s_mov_b64 vcc, 0x20000
	v_lshl_add_u64 v[154:155], v[154:155], 0, vcc
	s_waitcnt lgkmcnt(0)
	s_nop 0
	v_add_f32_e32 v211, v211, v212
	v_mov_b32_e32 v213, v211
	s_nop 1
	v_permlane32_swap_b32_e32 v211, v213
	s_and_saveexec_b64 s[22:23], s[0:1]
	s_cbranch_execz .Lp3e_5
	v_add_f32_e32 v211, v211, v213
	global_atomic_add_f32 v[206:207], v211, off offset:576
.Lp3e_5:
	s_or_b64 exec, exec, s[22:23]
	s_waitcnt vmcnt(12)
	v_pk_add_f32 v[30:31], v[30:31], v[160:161]
	v_pk_add_f32 v[28:29], v[28:29], v[158:159]
	global_store_dwordx4 v[154:155], v[28:31], off
	v_pk_add_f32 v[26:27], v[26:27], v[164:165]
	v_pk_add_f32 v[24:25], v[24:25], v[162:163]
	global_store_dwordx4 v[154:155], v[24:27], off offset:64
	v_pk_add_f32 v[22:23], v[22:23], v[168:169]
	v_pk_add_f32 v[20:21], v[20:21], v[166:167]
	global_store_dwordx4 v[154:155], v[20:23], off offset:512
	v_pk_add_f32 v[18:19], v[18:19], v[172:173]
	v_pk_add_f32 v[16:17], v[16:17], v[170:171]
	global_store_dwordx4 v[154:155], v[16:19], off offset:576
	v_mul_f32_e32 v208, v29, v29
	v_mul_f32_e32 v209, v31, v31
	v_fmac_f32_e32 v208, v28, v28
	v_fmac_f32_e32 v209, v30, v30
	v_add_f32_e32 v211, v208, v209
	v_mul_f32_e32 v208, v25, v25
	v_mul_f32_e32 v209, v27, v27
	v_fmac_f32_e32 v208, v24, v24
	v_fmac_f32_e32 v209, v26, v26
	v_add_f32_e32 v210, v208, v209
	v_add_f32_e32 v211, v211, v210
	v_mul_f32_e32 v208, v21, v21
	v_mul_f32_e32 v209, v23, v23
	v_fmac_f32_e32 v208, v20, v20
	v_fmac_f32_e32 v209, v22, v22
	v_add_f32_e32 v210, v208, v209
	v_add_f32_e32 v211, v211, v210
	v_mul_f32_e32 v208, v17, v17
	v_mul_f32_e32 v209, v19, v19
	v_fmac_f32_e32 v208, v16, v16
	v_fmac_f32_e32 v209, v18, v18
	v_add_f32_e32 v210, v208, v209
	v_add_f32_e32 v211, v211, v210
	ds_swizzle_b32 v212, v211 offset:swizzle(SWAP,16)
	s_mov_b64 vcc, 0x20000
	v_lshl_add_u64 v[154:155], v[154:155], 0, vcc
	s_waitcnt lgkmcnt(0)
	s_nop 0
	v_add_f32_e32 v211, v211, v212
	v_mov_b32_e32 v213, v211
	s_nop 1
	v_permlane32_swap_b32_e32 v211, v213
	s_and_saveexec_b64 s[22:23], s[0:1]
	s_cbranch_execz .Lp3e_6
	v_add_f32_e32 v211, v211, v213
	global_atomic_add_f32 v[206:207], v211, off offset:640
.Lp3e_6:
	s_or_b64 exec, exec, s[22:23]
	s_waitcnt vmcnt(8)
	v_pk_add_f32 v[14:15], v[14:15], v[176:177]
	v_pk_add_f32 v[12:13], v[12:13], v[174:175]
	global_store_dwordx4 v[154:155], v[12:15], off
	v_pk_add_f32 v[10:11], v[10:11], v[180:181]
	v_pk_add_f32 v[8:9], v[8:9], v[178:179]
	global_store_dwordx4 v[154:155], v[8:11], off offset:64
	v_pk_add_f32 v[6:7], v[6:7], v[184:185]
	v_pk_add_f32 v[4:5], v[4:5], v[182:183]
	global_store_dwordx4 v[154:155], v[4:7], off offset:512
	v_pk_add_f32 v[2:3], v[2:3], v[188:189]
	v_pk_add_f32 v[0:1], v[0:1], v[186:187]
	global_store_dwordx4 v[154:155], v[0:3], off offset:576
	v_mul_f32_e32 v208, v13, v13
	v_mul_f32_e32 v209, v15, v15
	v_fmac_f32_e32 v208, v12, v12
	v_fmac_f32_e32 v209, v14, v14
	v_add_f32_e32 v211, v208, v209
	v_mul_f32_e32 v208, v9, v9
	v_mul_f32_e32 v209, v11, v11
	v_fmac_f32_e32 v208, v8, v8
	v_fmac_f32_e32 v209, v10, v10
	v_add_f32_e32 v210, v208, v209
	v_add_f32_e32 v211, v211, v210
	v_mul_f32_e32 v208, v5, v5
	v_mul_f32_e32 v209, v7, v7
	v_fmac_f32_e32 v208, v4, v4
	v_fmac_f32_e32 v209, v6, v6
	v_add_f32_e32 v210, v208, v209
	v_add_f32_e32 v211, v211, v210
	v_mul_f32_e32 v208, v1, v1
	v_mul_f32_e32 v209, v3, v3
	v_fmac_f32_e32 v208, v0, v0
	v_fmac_f32_e32 v209, v2, v2
	v_add_f32_e32 v210, v208, v209
	v_add_f32_e32 v211, v211, v210
	ds_swizzle_b32 v212, v211 offset:swizzle(SWAP,16)
	s_waitcnt lgkmcnt(0)
	s_nop 0
	v_add_f32_e32 v211, v211, v212
	v_mov_b32_e32 v213, v211
	s_nop 1
	v_permlane32_swap_b32_e32 v211, v213
	s_and_saveexec_b64 s[20:21], s[0:1]
	s_cbranch_execz .LBB0_455
	v_add_f32_e32 v211, v211, v213
	global_atomic_add_f32 v[206:207], v211, off offset:704
